# P3 epilogue: hoist 16 residual loads to epilogue top, counted vmcnt
# speedup vs baseline: 1.0022x; 1.0022x over previous
; __device__ __forceinline__ unsigned pkh(float lo, float hi) { f32x2 v = {lo, hi}; h16x2 h = __builtin_convertvector(v, h16x2); return __builtin_bit_cast(unsigned, h); }
; __device__ __forceinline__ unsigned pk8(float a, float b, float c, float d) { int w = __builtin_amdgcn_cvt_pk_fp8_f32(a, b, 0, false); w = __builtin_amdgcn_cvt_pk_fp8_f32(c, d, w, true); return (unsigned)w; }
;     __device__ __forceinline__ void operator()(f32x4 (&acc)[2][2][4][2], const Unit& u, const Order& S, int wr, int wc, int fr_, int fq_, LAS unsigned char*, int) const {
;     ...
;                 const int row = row0 + ai * HALF + m * 16; const size_t off = (size_t)row * DM + col0;
;                 float sq = 0.f;
; #pragma unroll
;                 for (int bj = 0; bj < 2; ++bj) {
;                     const h16x8 bs = *(const h16x8*)(h16 + off + bj * HALF);
;                     f32x4 o0 = acc[ai][bj][m][0] * pre, o1 = acc[ai][bj][m][1] * pre;
; #pragma unroll
;                     for (int e = 0; e < 4; ++e) { o0[e] += (float)bs[e]; o1[e] += (float)bs[4 + e]; }
;                     if (out32) { if (!dry) { __builtin_nontemporal_store(o0, (f32x4*)(out32 + off + bj * HALF)); __builtin_nontemporal_store(o1, (f32x4*)(out32 + off + bj * HALF + 4)); } }
;                     else if (!dry) {
;                         sq += (o0[0] * o0[0] + o0[1] * o0[1]) + (o0[2] * o0[2] + o0[3] * o0[3]) + (o1[0] * o1[0] + o1[1] * o1[1]) + (o1[2] * o1[2] + o1[3] * o1[3]);
;                         u32x4 w; w.x = pkh(o0[0], o0[1]); w.y = pkh(o0[2], o0[3]); w.z = pkh(o1[0], o1[1]); w.w = pkh(o1[2], o1[3]);
;                         *(u32x4*)(h16 + off + bj * HALF) = w;
;                         if (h8) { u32x2 q; q.x = pk8(o0[0] * F8_SA, o0[1] * F8_SA, o0[2] * F8_SA, o0[3] * F8_SA); q.y = pk8(o1[0] * F8_SA, o1[1] * F8_SA, o1[2] * F8_SA, o1[3] * F8_SA); *(u32x2*)(h8 + off + bj * HALF) = q; } }
;                 }
;                 if (!out32 && !dry) { sq += __shfl_xor(sq, 16); sq += __shfl_xor(sq, 32); if (fq == 0) atomicAdd(ss_out + row, sq); }
.LBB0_403:
	s_lshl_b32 s3, s45, 8
	v_mov_b32_e32 v146, v150
	v_mov_b32_e32 v168, v1
	s_add_i32 s3, s3, s38
	s_lshl_b32 s2, s2, 8
	v_add_u32_e32 v148, s3, v146
	s_or_b32 s2, s2, s39
	v_ashrrev_i32_e32 v149, 31, v148
	v_lshl_add_u32 v146, v168, 3, s2
	v_lshlrev_b64 v[156:157], 11, v[148:149]
	v_ashrrev_i32_e32 v147, 31, v146
	v_lshl_add_u64 v[156:157], s[90:91], 0, v[156:157]
	v_lshl_add_u64 v[166:167], v[146:147], 1, v[156:157]
	global_load_dwordx4 v[158:161], v[166:167], off
	global_load_dwordx4 v[162:165], v[166:167], off offset:256
	s_mov_b32 s99, 0
	s_mov_b32 s98, 0x8000
	v_lshl_add_u64 v[170:171], s[98:99], 0, v[166:167]
	global_load_dwordx4 v[176:179], v[170:171], off
	global_load_dwordx4 v[180:183], v[170:171], off offset:256
	s_mov_b32 s98, 0x10000
	v_lshl_add_u64 v[170:171], s[98:99], 0, v[166:167]
	global_load_dwordx4 v[184:187], v[170:171], off
	global_load_dwordx4 v[188:191], v[170:171], off offset:256
	s_mov_b32 s98, 0x18000
	v_lshl_add_u64 v[170:171], s[98:99], 0, v[166:167]
	global_load_dwordx4 v[192:195], v[170:171], off
	global_load_dwordx4 v[196:199], v[170:171], off offset:256
	s_mov_b32 s98, 0x40000
	v_lshl_add_u64 v[170:171], s[98:99], 0, v[166:167]
	global_load_dwordx4 v[200:203], v[170:171], off
	global_load_dwordx4 v[208:211], v[170:171], off offset:256
	s_mov_b32 s98, 0x48000
	v_lshl_add_u64 v[170:171], s[98:99], 0, v[166:167]
	global_load_dwordx4 v[212:215], v[170:171], off
	global_load_dwordx4 v[216:219], v[170:171], off offset:256
	s_mov_b32 s98, 0x50000
	v_lshl_add_u64 v[170:171], s[98:99], 0, v[166:167]
	global_load_dwordx4 v[240:243], v[170:171], off
	global_load_dwordx4 v[244:247], v[170:171], off offset:256
	s_mov_b32 s98, 0x58000
	v_lshl_add_u64 v[170:171], s[98:99], 0, v[166:167]
	global_load_dwordx4 v[248:251], v[170:171], off
	global_load_dwordx4 v[252:255], v[170:171], off offset:256
	v_and_b32_e32 v157, 64, v155
	v_xor_b32_e32 v156, 16, v155
	v_add_u32_e32 v157, 64, v157
	v_xor_b32_e32 v169, 32, v155
	v_cmp_lt_i32_e64 s[2:3], v156, v157
	v_cmp_eq_u32_e32 vcc, 0, v168
	s_waitcnt vmcnt(14)
	v_cvt_f32_f16_e32 v168, v158
	v_cndmask_b32_e64 v156, v155, v156, s[2:3]
	v_cmp_lt_i32_e64 s[2:3], v169, v157
	v_cvt_f32_f16_e32 v172, v162
	v_cvt_f32_f16_sdwa v173, v162 dst_sel:DWORD dst_unused:UNUSED_PAD src0_sel:WORD_1
	v_cndmask_b32_e64 v157, v155, v169, s[2:3]
	v_cvt_f32_f16_sdwa v169, v158 dst_sel:DWORD dst_unused:UNUSED_PAD src0_sel:WORD_1
	v_cvt_f32_f16_e32 v158, v159
	v_cvt_f32_f16_sdwa v159, v159 dst_sel:DWORD dst_unused:UNUSED_PAD src0_sel:WORD_1
	v_cvt_f32_f16_e32 v162, v163
	v_cvt_f32_f16_sdwa v163, v163 dst_sel:DWORD dst_unused:UNUSED_PAD src0_sel:WORD_1
	v_cvt_f32_f16_e32 v170, v160
	v_cvt_f32_f16_sdwa v171, v160 dst_sel:DWORD dst_unused:UNUSED_PAD src0_sel:WORD_1
	v_cvt_f32_f16_e32 v160, v161
	v_cvt_f32_f16_sdwa v161, v161 dst_sel:DWORD dst_unused:UNUSED_PAD src0_sel:WORD_1
	v_cvt_f32_f16_e32 v174, v164
	v_cvt_f32_f16_sdwa v175, v164 dst_sel:DWORD dst_unused:UNUSED_PAD src0_sel:WORD_1
	v_cvt_f32_f16_e32 v164, v165
	v_cvt_f32_f16_sdwa v165, v165 dst_sel:DWORD dst_unused:UNUSED_PAD src0_sel:WORD_1
	v_pk_add_f32 v[126:127], v[126:127], v[168:169]
	v_pk_add_f32 v[128:129], v[128:129], v[158:159]
	v_pk_add_f32 v[118:119], v[118:119], v[172:173]
	v_pk_add_f32 v[120:121], v[120:121], v[162:163]
	v_pk_add_f32 v[122:123], v[122:123], v[170:171]
	v_pk_add_f32 v[124:125], v[124:125], v[160:161]
	v_pk_add_f32 v[158:159], v[114:115], v[174:175]
	v_pk_add_f32 v[160:161], v[116:117], v[164:165]
	v_pk_mul_f32 v[116:117], v[126:127], v[126:127]
	v_pk_mul_f32 v[162:163], v[128:129], v[128:129]
	v_cvt_pk_f16_f32 v114, v126, v127
	v_cvt_pk_f16_f32 v115, v128, v129
	v_pk_mul_f32 v[126:127], v[118:119], v[118:119]
	v_pk_mul_f32 v[128:129], v[120:121], v[120:121]
	v_pk_mul_f32 v[164:165], v[122:123], v[122:123]
	v_pk_mul_f32 v[170:171], v[158:159], v[158:159]
	v_add_f32_e32 v128, v128, v129
	v_add_f32_e32 v126, v126, v127
	v_add_f32_e32 v162, v162, v163
	v_add_f32_e32 v116, v116, v117
	v_pk_mul_f32 v[168:169], v[124:125], v[124:125]
	v_pk_mul_f32 v[172:173], v[160:161], v[160:161]
	v_add_f32_e32 v127, v170, v171
	v_add_f32_e32 v117, v164, v165
	v_add_f32_e32 v126, v126, v128
	v_add_f32_e32 v116, v116, v162
	v_add_f32_e32 v129, v172, v173
	v_add_f32_e32 v163, v168, v169
	v_add_f32_e32 v126, v127, v126
	v_add_f32_e32 v116, v117, v116
	v_add_f32_e32 v117, v129, v126
	v_add_f32_e32 v116, v163, v116
	v_lshlrev_b32_e32 v156, 2, v156
	v_add_f32_e32 v126, v116, v117
	ds_bpermute_b32 v127, v156, v126
	v_cvt_pk_f16_f32 v116, v122, v123
	v_cvt_pk_f16_f32 v117, v124, v125
	global_store_dwordx4 v[166:167], v[114:117], off
	v_cvt_pk_f16_f32 v118, v118, v119
	v_cvt_pk_f16_f32 v119, v120, v121
	s_waitcnt lgkmcnt(0)
	v_add_f32_e32 v114, v126, v127
	v_lshlrev_b32_e32 v116, 2, v157
	ds_bpermute_b32 v115, v116, v114
	v_cvt_pk_f16_f32 v120, v158, v159
	v_cvt_pk_f16_f32 v121, v160, v161
	global_store_dwordx4 v[166:167], v[118:121], off offset:256
	s_and_saveexec_b64 s[2:3], vcc
	s_cbranch_execz .LBB0_405
	v_lshl_add_u64 v[118:119], v[148:149], 2, s[18:19]
	s_waitcnt lgkmcnt(0)
	v_add_f32_e32 v114, v114, v115
	global_atomic_add_f32 v[118:119], v114, off
; __device__ __forceinline__ unsigned pkh(float lo, float hi) { f32x2 v = {lo, hi}; h16x2 h = __builtin_convertvector(v, h16x2); return __builtin_bit_cast(unsigned, h); }
; __device__ __forceinline__ unsigned pk8(float a, float b, float c, float d) { int w = __builtin_amdgcn_cvt_pk_fp8_f32(a, b, 0, false); w = __builtin_amdgcn_cvt_pk_fp8_f32(c, d, w, true); return (unsigned)w; }
;     __device__ __forceinline__ void operator()(f32x4 (&acc)[2][2][4][2], const Unit& u, const Order& S, int wr, int wc, int fr_, int fq_, LAS unsigned char*, int) const {
;     ...
;                 const int row = row0 + ai * HALF + m * 16; const size_t off = (size_t)row * DM + col0;
;                 float sq = 0.f;
; #pragma unroll
;                 for (int bj = 0; bj < 2; ++bj) {
;                     const h16x8 bs = *(const h16x8*)(h16 + off + bj * HALF);
;                     f32x4 o0 = acc[ai][bj][m][0] * pre, o1 = acc[ai][bj][m][1] * pre;
; #pragma unroll
;                     for (int e = 0; e < 4; ++e) { o0[e] += (float)bs[e]; o1[e] += (float)bs[4 + e]; }
;                     if (out32) { if (!dry) { __builtin_nontemporal_store(o0, (f32x4*)(out32 + off + bj * HALF)); __builtin_nontemporal_store(o1, (f32x4*)(out32 + off + bj * HALF + 4)); } }
;                     else if (!dry) {
;                         sq += (o0[0] * o0[0] + o0[1] * o0[1]) + (o0[2] * o0[2] + o0[3] * o0[3]) + (o1[0] * o1[0] + o1[1] * o1[1]) + (o1[2] * o1[2] + o1[3] * o1[3]);
;                         u32x4 w; w.x = pkh(o0[0], o0[1]); w.y = pkh(o0[2], o0[3]); w.z = pkh(o1[0], o1[1]); w.w = pkh(o1[2], o1[3]);
;                         *(u32x4*)(h16 + off + bj * HALF) = w;
;                         if (h8) { u32x2 q; q.x = pk8(o0[0] * F8_SA, o0[1] * F8_SA, o0[2] * F8_SA, o0[3] * F8_SA); q.y = pk8(o1[0] * F8_SA, o1[1] * F8_SA, o1[2] * F8_SA, o1[3] * F8_SA); *(u32x2*)(h8 + off + bj * HALF) = q; } }
;                 }
;                 if (!out32 && !dry) { sq += __shfl_xor(sq, 16); sq += __shfl_xor(sq, 32); if (fq == 0) atomicAdd(ss_out + row, sq); }
.LBB0_405:
	s_or_b64 exec, exec, s[2:3]
	v_add_u32_e32 v114, 16, v148
	s_waitcnt lgkmcnt(0)
	v_ashrrev_i32_e32 v115, 31, v114
	v_lshlrev_b64 v[118:119], 11, v[114:115]
	v_lshl_add_u64 v[118:119], s[90:91], 0, v[118:119]
	v_lshl_add_u64 v[126:127], v[146:147], 1, v[118:119]
	s_waitcnt vmcnt(15)
	v_cvt_f32_f16_e32 v128, v176
	v_cvt_f32_f16_sdwa v129, v176 dst_sel:DWORD dst_unused:UNUSED_PAD src0_sel:WORD_1
	v_cvt_f32_f16_e32 v118, v177
	v_cvt_f32_f16_sdwa v119, v177 dst_sel:DWORD dst_unused:UNUSED_PAD src0_sel:WORD_1
	s_waitcnt vmcnt(14)
	v_cvt_f32_f16_e32 v160, v180
	v_cvt_f32_f16_sdwa v161, v180 dst_sel:DWORD dst_unused:UNUSED_PAD src0_sel:WORD_1
	v_cvt_f32_f16_e32 v122, v181
	v_cvt_f32_f16_sdwa v123, v181 dst_sel:DWORD dst_unused:UNUSED_PAD src0_sel:WORD_1
	v_cvt_f32_f16_e32 v158, v178
	v_cvt_f32_f16_sdwa v159, v178 dst_sel:DWORD dst_unused:UNUSED_PAD src0_sel:WORD_1
	v_cvt_f32_f16_e32 v120, v179
	v_cvt_f32_f16_sdwa v121, v179 dst_sel:DWORD dst_unused:UNUSED_PAD src0_sel:WORD_1
	v_cvt_f32_f16_e32 v162, v182
	v_cvt_f32_f16_sdwa v163, v182 dst_sel:DWORD dst_unused:UNUSED_PAD src0_sel:WORD_1
	v_cvt_f32_f16_e32 v124, v183
	v_cvt_f32_f16_sdwa v125, v183 dst_sel:DWORD dst_unused:UNUSED_PAD src0_sel:WORD_1
	v_pk_add_f32 v[110:111], v[110:111], v[128:129]
	v_pk_add_f32 v[112:113], v[112:113], v[118:119]
	v_pk_add_f32 v[102:103], v[102:103], v[160:161]
	v_pk_add_f32 v[104:105], v[104:105], v[122:123]
	v_pk_add_f32 v[106:107], v[106:107], v[158:159]
	v_pk_add_f32 v[108:109], v[108:109], v[120:121]
	v_pk_add_f32 v[118:119], v[98:99], v[162:163]
	v_pk_add_f32 v[120:121], v[100:101], v[124:125]
	v_pk_mul_f32 v[100:101], v[110:111], v[110:111]
	v_pk_mul_f32 v[122:123], v[112:113], v[112:113]
	v_cvt_pk_f16_f32 v98, v110, v111
	v_cvt_pk_f16_f32 v99, v112, v113
	v_pk_mul_f32 v[110:111], v[102:103], v[102:103]
	v_pk_mul_f32 v[112:113], v[104:105], v[104:105]
	v_pk_mul_f32 v[124:125], v[106:107], v[106:107]
	v_pk_mul_f32 v[158:159], v[118:119], v[118:119]
	v_add_f32_e32 v112, v112, v113
	v_add_f32_e32 v110, v110, v111
	v_add_f32_e32 v117, v122, v123
	v_add_f32_e32 v100, v100, v101
	v_pk_mul_f32 v[128:129], v[108:109], v[108:109]
	v_pk_mul_f32 v[160:161], v[120:121], v[120:121]
	v_add_f32_e32 v111, v158, v159
	v_add_f32_e32 v101, v124, v125
	v_add_f32_e32 v110, v110, v112
	v_add_f32_e32 v100, v100, v117
	v_add_f32_e32 v113, v160, v161
	v_add_f32_e32 v122, v128, v129
	v_add_f32_e32 v110, v111, v110
	v_add_f32_e32 v100, v101, v100
	v_add_f32_e32 v101, v113, v110
	v_add_f32_e32 v100, v122, v100
	v_add_f32_e32 v110, v100, v101
	ds_bpermute_b32 v111, v156, v110
	v_cvt_pk_f16_f32 v100, v106, v107
	v_cvt_pk_f16_f32 v101, v108, v109
	global_store_dwordx4 v[126:127], v[98:101], off
	s_waitcnt lgkmcnt(0)
	s_nop 0
	v_add_f32_e32 v98, v110, v111
	ds_bpermute_b32 v99, v116, v98
	v_cvt_pk_f16_f32 v100, v102, v103
	v_cvt_pk_f16_f32 v101, v104, v105
	v_cvt_pk_f16_f32 v102, v118, v119
	v_cvt_pk_f16_f32 v103, v120, v121
	global_store_dwordx4 v[126:127], v[100:103], off offset:256
	s_and_saveexec_b64 s[2:3], vcc
	s_cbranch_execz .LBB0_407
	v_lshl_add_u64 v[100:101], v[114:115], 2, s[18:19]
	s_waitcnt lgkmcnt(0)
	v_add_f32_e32 v98, v98, v99
	global_atomic_add_f32 v[100:101], v98, off
.LBB0_407:
	s_or_b64 exec, exec, s[2:3]
	v_add_u32_e32 v98, 32, v148
	s_waitcnt lgkmcnt(0)
	v_ashrrev_i32_e32 v99, 31, v98
	v_lshlrev_b64 v[100:101], 11, v[98:99]
	v_lshl_add_u64 v[100:101], s[90:91], 0, v[100:101]
	v_lshl_add_u64 v[108:109], v[146:147], 1, v[100:101]
	s_waitcnt vmcnt(15)
	v_cvt_f32_f16_e32 v110, v184
	v_cvt_f32_f16_sdwa v111, v184 dst_sel:DWORD dst_unused:UNUSED_PAD src0_sel:WORD_1
	v_cvt_f32_f16_e32 v100, v185
	v_cvt_f32_f16_sdwa v101, v185 dst_sel:DWORD dst_unused:UNUSED_PAD src0_sel:WORD_1
	s_waitcnt vmcnt(14)
	v_cvt_f32_f16_e32 v114, v188
	v_cvt_f32_f16_sdwa v115, v188 dst_sel:DWORD dst_unused:UNUSED_PAD src0_sel:WORD_1
	v_cvt_f32_f16_e32 v104, v189
	v_cvt_f32_f16_sdwa v105, v189 dst_sel:DWORD dst_unused:UNUSED_PAD src0_sel:WORD_1
	v_cvt_f32_f16_e32 v112, v186
	v_cvt_f32_f16_sdwa v113, v186 dst_sel:DWORD dst_unused:UNUSED_PAD src0_sel:WORD_1
	v_cvt_f32_f16_e32 v102, v187
	v_cvt_f32_f16_sdwa v103, v187 dst_sel:DWORD dst_unused:UNUSED_PAD src0_sel:WORD_1
	v_cvt_f32_f16_e32 v118, v190
	v_cvt_f32_f16_sdwa v119, v190 dst_sel:DWORD dst_unused:UNUSED_PAD src0_sel:WORD_1
	v_cvt_f32_f16_e32 v106, v191
	v_cvt_f32_f16_sdwa v107, v191 dst_sel:DWORD dst_unused:UNUSED_PAD src0_sel:WORD_1
	v_pk_add_f32 v[94:95], v[94:95], v[110:111]
	v_pk_add_f32 v[96:97], v[96:97], v[100:101]
	v_pk_add_f32 v[86:87], v[86:87], v[114:115]
	v_pk_add_f32 v[88:89], v[88:89], v[104:105]
	v_pk_add_f32 v[90:91], v[90:91], v[112:113]
	v_pk_add_f32 v[92:93], v[92:93], v[102:103]
	v_pk_add_f32 v[100:101], v[82:83], v[118:119]
	v_pk_add_f32 v[102:103], v[84:85], v[106:107]
	v_pk_mul_f32 v[84:85], v[94:95], v[94:95]
	v_pk_mul_f32 v[104:105], v[96:97], v[96:97]
	v_cvt_pk_f16_f32 v82, v94, v95
	v_cvt_pk_f16_f32 v83, v96, v97
	v_pk_mul_f32 v[94:95], v[86:87], v[86:87]
	v_pk_mul_f32 v[96:97], v[88:89], v[88:89]
	v_pk_mul_f32 v[106:107], v[90:91], v[90:91]
	v_pk_mul_f32 v[112:113], v[100:101], v[100:101]
	v_add_f32_e32 v96, v96, v97
	v_add_f32_e32 v94, v94, v95
	v_add_f32_e32 v104, v104, v105
	v_add_f32_e32 v84, v84, v85
	v_pk_mul_f32 v[110:111], v[92:93], v[92:93]
	v_pk_mul_f32 v[114:115], v[102:103], v[102:103]
	v_add_f32_e32 v95, v112, v113
	v_add_f32_e32 v85, v106, v107
	v_add_f32_e32 v94, v94, v96
	v_add_f32_e32 v84, v84, v104
	v_add_f32_e32 v97, v114, v115
	v_add_f32_e32 v105, v110, v111
	v_add_f32_e32 v94, v95, v94
	v_add_f32_e32 v84, v85, v84
	v_add_f32_e32 v85, v97, v94
	v_add_f32_e32 v84, v105, v84
	v_add_f32_e32 v94, v84, v85
	ds_bpermute_b32 v95, v156, v94
	v_cvt_pk_f16_f32 v84, v90, v91
	v_cvt_pk_f16_f32 v85, v92, v93
	global_store_dwordx4 v[108:109], v[82:85], off
	s_waitcnt lgkmcnt(0)
	s_nop 0
	v_add_f32_e32 v82, v94, v95
	ds_bpermute_b32 v83, v116, v82
	v_cvt_pk_f16_f32 v84, v86, v87
	v_cvt_pk_f16_f32 v85, v88, v89
	v_cvt_pk_f16_f32 v86, v100, v101
	v_cvt_pk_f16_f32 v87, v102, v103
	global_store_dwordx4 v[108:109], v[84:87], off offset:256
	s_and_saveexec_b64 s[2:3], vcc
	s_cbranch_execz .LBB0_409
	v_lshl_add_u64 v[84:85], v[98:99], 2, s[18:19]
	s_waitcnt lgkmcnt(0)
	v_add_f32_e32 v82, v82, v83
	global_atomic_add_f32 v[84:85], v82, off
; __device__ __forceinline__ unsigned pkh(float lo, float hi) { f32x2 v = {lo, hi}; h16x2 h = __builtin_convertvector(v, h16x2); return __builtin_bit_cast(unsigned, h); }
; __device__ __forceinline__ unsigned pk8(float a, float b, float c, float d) { int w = __builtin_amdgcn_cvt_pk_fp8_f32(a, b, 0, false); w = __builtin_amdgcn_cvt_pk_fp8_f32(c, d, w, true); return (unsigned)w; }
;     __device__ __forceinline__ void operator()(f32x4 (&acc)[2][2][4][2], const Unit& u, const Order& S, int wr, int wc, int fr_, int fq_, LAS unsigned char*, int) const {
;     ...
;                 const int row = row0 + ai * HALF + m * 16; const size_t off = (size_t)row * DM + col0;
;                 float sq = 0.f;
; #pragma unroll
;                 for (int bj = 0; bj < 2; ++bj) {
;                     const h16x8 bs = *(const h16x8*)(h16 + off + bj * HALF);
;                     f32x4 o0 = acc[ai][bj][m][0] * pre, o1 = acc[ai][bj][m][1] * pre;
; #pragma unroll
;                     for (int e = 0; e < 4; ++e) { o0[e] += (float)bs[e]; o1[e] += (float)bs[4 + e]; }
;                     if (out32) { if (!dry) { __builtin_nontemporal_store(o0, (f32x4*)(out32 + off + bj * HALF)); __builtin_nontemporal_store(o1, (f32x4*)(out32 + off + bj * HALF + 4)); } }
;                     else if (!dry) {
;                         sq += (o0[0] * o0[0] + o0[1] * o0[1]) + (o0[2] * o0[2] + o0[3] * o0[3]) + (o1[0] * o1[0] + o1[1] * o1[1]) + (o1[2] * o1[2] + o1[3] * o1[3]);
;                         u32x4 w; w.x = pkh(o0[0], o0[1]); w.y = pkh(o0[2], o0[3]); w.z = pkh(o1[0], o1[1]); w.w = pkh(o1[2], o1[3]);
;                         *(u32x4*)(h16 + off + bj * HALF) = w;
;                         if (h8) { u32x2 q; q.x = pk8(o0[0] * F8_SA, o0[1] * F8_SA, o0[2] * F8_SA, o0[3] * F8_SA); q.y = pk8(o1[0] * F8_SA, o1[1] * F8_SA, o1[2] * F8_SA, o1[3] * F8_SA); *(u32x2*)(h8 + off + bj * HALF) = q; } }
;                 }
;                 if (!out32 && !dry) { sq += __shfl_xor(sq, 16); sq += __shfl_xor(sq, 32); if (fq == 0) atomicAdd(ss_out + row, sq); }
.LBB0_409:
	s_or_b64 exec, exec, s[2:3]
	v_add_u32_e32 v82, 48, v148
	s_waitcnt lgkmcnt(0)
	v_ashrrev_i32_e32 v83, 31, v82
	v_lshlrev_b64 v[84:85], 11, v[82:83]
	v_lshl_add_u64 v[84:85], s[90:91], 0, v[84:85]
	v_lshl_add_u64 v[92:93], v[146:147], 1, v[84:85]
	s_waitcnt vmcnt(15)
	v_cvt_f32_f16_e32 v94, v192
	v_cvt_f32_f16_sdwa v95, v192 dst_sel:DWORD dst_unused:UNUSED_PAD src0_sel:WORD_1
	v_cvt_f32_f16_e32 v84, v193
	v_cvt_f32_f16_sdwa v85, v193 dst_sel:DWORD dst_unused:UNUSED_PAD src0_sel:WORD_1
	s_waitcnt vmcnt(14)
	v_cvt_f32_f16_e32 v98, v196
	v_cvt_f32_f16_sdwa v99, v196 dst_sel:DWORD dst_unused:UNUSED_PAD src0_sel:WORD_1
	v_cvt_f32_f16_e32 v88, v197
	v_cvt_f32_f16_sdwa v89, v197 dst_sel:DWORD dst_unused:UNUSED_PAD src0_sel:WORD_1
	v_cvt_f32_f16_e32 v96, v194
	v_cvt_f32_f16_sdwa v97, v194 dst_sel:DWORD dst_unused:UNUSED_PAD src0_sel:WORD_1
	v_cvt_f32_f16_e32 v86, v195
	v_cvt_f32_f16_sdwa v87, v195 dst_sel:DWORD dst_unused:UNUSED_PAD src0_sel:WORD_1
	v_cvt_f32_f16_e32 v100, v198
	v_cvt_f32_f16_sdwa v101, v198 dst_sel:DWORD dst_unused:UNUSED_PAD src0_sel:WORD_1
	v_cvt_f32_f16_e32 v90, v199
	v_cvt_f32_f16_sdwa v91, v199 dst_sel:DWORD dst_unused:UNUSED_PAD src0_sel:WORD_1
	v_pk_add_f32 v[78:79], v[78:79], v[94:95]
	v_pk_add_f32 v[80:81], v[80:81], v[84:85]
	v_pk_add_f32 v[70:71], v[70:71], v[98:99]
	v_pk_add_f32 v[72:73], v[72:73], v[88:89]
	v_pk_add_f32 v[74:75], v[74:75], v[96:97]
	v_pk_add_f32 v[76:77], v[76:77], v[86:87]
	v_pk_add_f32 v[84:85], v[66:67], v[100:101]
	v_pk_add_f32 v[86:87], v[68:69], v[90:91]
	v_pk_mul_f32 v[68:69], v[78:79], v[78:79]
	v_pk_mul_f32 v[88:89], v[80:81], v[80:81]
	v_cvt_pk_f16_f32 v66, v78, v79
	v_cvt_pk_f16_f32 v67, v80, v81
	v_pk_mul_f32 v[78:79], v[70:71], v[70:71]
	v_pk_mul_f32 v[80:81], v[72:73], v[72:73]
	v_pk_mul_f32 v[90:91], v[74:75], v[74:75]
	v_pk_mul_f32 v[96:97], v[84:85], v[84:85]
	v_add_f32_e32 v80, v80, v81
	v_add_f32_e32 v78, v78, v79
	v_add_f32_e32 v88, v88, v89
	v_add_f32_e32 v68, v68, v69
	v_pk_mul_f32 v[94:95], v[76:77], v[76:77]
	v_pk_mul_f32 v[98:99], v[86:87], v[86:87]
	v_add_f32_e32 v79, v96, v97
	v_add_f32_e32 v69, v90, v91
	v_add_f32_e32 v78, v78, v80
	v_add_f32_e32 v68, v68, v88
	v_add_f32_e32 v81, v98, v99
	v_add_f32_e32 v89, v94, v95
	v_add_f32_e32 v78, v79, v78
	v_add_f32_e32 v68, v69, v68
	v_add_f32_e32 v69, v81, v78
	v_add_f32_e32 v68, v89, v68
	v_add_f32_e32 v78, v68, v69
	ds_bpermute_b32 v79, v156, v78
	v_cvt_pk_f16_f32 v68, v74, v75
	v_cvt_pk_f16_f32 v69, v76, v77
	global_store_dwordx4 v[92:93], v[66:69], off
	s_waitcnt lgkmcnt(0)
	s_nop 0
	v_add_f32_e32 v66, v78, v79
	ds_bpermute_b32 v67, v116, v66
	v_cvt_pk_f16_f32 v68, v70, v71
	v_cvt_pk_f16_f32 v69, v72, v73
	v_cvt_pk_f16_f32 v70, v84, v85
	v_cvt_pk_f16_f32 v71, v86, v87
	global_store_dwordx4 v[92:93], v[68:71], off offset:256
	s_and_saveexec_b64 s[2:3], vcc
	s_cbranch_execz .LBB0_411
	v_lshl_add_u64 v[68:69], v[82:83], 2, s[18:19]
	s_waitcnt lgkmcnt(0)
	v_add_f32_e32 v66, v66, v67
	global_atomic_add_f32 v[68:69], v66, off
.LBB0_411:
	s_or_b64 exec, exec, s[2:3]
	v_add_u32_e32 v66, 0x80, v148
	s_waitcnt lgkmcnt(0)
	v_ashrrev_i32_e32 v67, 31, v66
	v_lshlrev_b64 v[68:69], 11, v[66:67]
	v_lshl_add_u64 v[68:69], s[90:91], 0, v[68:69]
	v_lshl_add_u64 v[76:77], v[146:147], 1, v[68:69]
	s_waitcnt vmcnt(15)
	v_cvt_f32_f16_e32 v78, v200
	v_cvt_f32_f16_sdwa v79, v200 dst_sel:DWORD dst_unused:UNUSED_PAD src0_sel:WORD_1
	v_cvt_f32_f16_e32 v68, v201
	v_cvt_f32_f16_sdwa v69, v201 dst_sel:DWORD dst_unused:UNUSED_PAD src0_sel:WORD_1
	s_waitcnt vmcnt(14)
	v_cvt_f32_f16_e32 v82, v208
	v_cvt_f32_f16_sdwa v83, v208 dst_sel:DWORD dst_unused:UNUSED_PAD src0_sel:WORD_1
	v_cvt_f32_f16_e32 v72, v209
	v_cvt_f32_f16_sdwa v73, v209 dst_sel:DWORD dst_unused:UNUSED_PAD src0_sel:WORD_1
	v_cvt_f32_f16_e32 v80, v202
	v_cvt_f32_f16_sdwa v81, v202 dst_sel:DWORD dst_unused:UNUSED_PAD src0_sel:WORD_1
	v_cvt_f32_f16_e32 v70, v203
	v_cvt_f32_f16_sdwa v71, v203 dst_sel:DWORD dst_unused:UNUSED_PAD src0_sel:WORD_1
	v_cvt_f32_f16_e32 v84, v210
	v_cvt_f32_f16_sdwa v85, v210 dst_sel:DWORD dst_unused:UNUSED_PAD src0_sel:WORD_1
	v_cvt_f32_f16_e32 v74, v211
	v_cvt_f32_f16_sdwa v75, v211 dst_sel:DWORD dst_unused:UNUSED_PAD src0_sel:WORD_1
	v_pk_add_f32 v[62:63], v[62:63], v[78:79]
	v_pk_add_f32 v[64:65], v[64:65], v[68:69]
	v_pk_add_f32 v[54:55], v[54:55], v[82:83]
	v_pk_add_f32 v[56:57], v[56:57], v[72:73]
	v_pk_add_f32 v[58:59], v[58:59], v[80:81]
	v_pk_add_f32 v[60:61], v[60:61], v[70:71]
	v_pk_add_f32 v[68:69], v[50:51], v[84:85]
	v_pk_add_f32 v[70:71], v[52:53], v[74:75]
	v_pk_mul_f32 v[52:53], v[62:63], v[62:63]
	v_pk_mul_f32 v[72:73], v[64:65], v[64:65]
	v_cvt_pk_f16_f32 v50, v62, v63
	v_cvt_pk_f16_f32 v51, v64, v65
	v_pk_mul_f32 v[62:63], v[54:55], v[54:55]
	v_pk_mul_f32 v[64:65], v[56:57], v[56:57]
	v_pk_mul_f32 v[74:75], v[58:59], v[58:59]
	v_pk_mul_f32 v[80:81], v[68:69], v[68:69]
	v_add_f32_e32 v64, v64, v65
	v_add_f32_e32 v62, v62, v63
	v_add_f32_e32 v72, v72, v73
	v_add_f32_e32 v52, v52, v53
	v_pk_mul_f32 v[78:79], v[60:61], v[60:61]
	v_pk_mul_f32 v[82:83], v[70:71], v[70:71]
	v_add_f32_e32 v63, v80, v81
	v_add_f32_e32 v53, v74, v75
	v_add_f32_e32 v62, v62, v64
	v_add_f32_e32 v52, v52, v72
	v_add_f32_e32 v65, v82, v83
	v_add_f32_e32 v73, v78, v79
	v_add_f32_e32 v62, v63, v62
	v_add_f32_e32 v52, v53, v52
	v_add_f32_e32 v53, v65, v62
	v_add_f32_e32 v52, v73, v52
	v_add_f32_e32 v62, v52, v53
	ds_bpermute_b32 v63, v156, v62
	v_cvt_pk_f16_f32 v52, v58, v59
	v_cvt_pk_f16_f32 v53, v60, v61
	global_store_dwordx4 v[76:77], v[50:53], off
	s_waitcnt lgkmcnt(0)
	s_nop 0
	v_add_f32_e32 v50, v62, v63
	ds_bpermute_b32 v51, v116, v50
	v_cvt_pk_f16_f32 v52, v54, v55
	v_cvt_pk_f16_f32 v53, v56, v57
	v_cvt_pk_f16_f32 v54, v68, v69
	v_cvt_pk_f16_f32 v55, v70, v71
	global_store_dwordx4 v[76:77], v[52:55], off offset:256
	s_and_saveexec_b64 s[2:3], vcc
	s_cbranch_execz .LBB0_413
	v_lshl_add_u64 v[52:53], v[66:67], 2, s[18:19]
	s_waitcnt lgkmcnt(0)
	v_add_f32_e32 v50, v50, v51
	global_atomic_add_f32 v[52:53], v50, off
; __device__ __forceinline__ unsigned pkh(float lo, float hi) { f32x2 v = {lo, hi}; h16x2 h = __builtin_convertvector(v, h16x2); return __builtin_bit_cast(unsigned, h); }
; __device__ __forceinline__ unsigned pk8(float a, float b, float c, float d) { int w = __builtin_amdgcn_cvt_pk_fp8_f32(a, b, 0, false); w = __builtin_amdgcn_cvt_pk_fp8_f32(c, d, w, true); return (unsigned)w; }
;     __device__ __forceinline__ void operator()(f32x4 (&acc)[2][2][4][2], const Unit& u, const Order& S, int wr, int wc, int fr_, int fq_, LAS unsigned char*, int) const {
;     ...
;                 const int row = row0 + ai * HALF + m * 16; const size_t off = (size_t)row * DM + col0;
;                 float sq = 0.f;
; #pragma unroll
;                 for (int bj = 0; bj < 2; ++bj) {
;                     const h16x8 bs = *(const h16x8*)(h16 + off + bj * HALF);
;                     f32x4 o0 = acc[ai][bj][m][0] * pre, o1 = acc[ai][bj][m][1] * pre;
; #pragma unroll
;                     for (int e = 0; e < 4; ++e) { o0[e] += (float)bs[e]; o1[e] += (float)bs[4 + e]; }
;                     if (out32) { if (!dry) { __builtin_nontemporal_store(o0, (f32x4*)(out32 + off + bj * HALF)); __builtin_nontemporal_store(o1, (f32x4*)(out32 + off + bj * HALF + 4)); } }
;                     else if (!dry) {
;                         sq += (o0[0] * o0[0] + o0[1] * o0[1]) + (o0[2] * o0[2] + o0[3] * o0[3]) + (o1[0] * o1[0] + o1[1] * o1[1]) + (o1[2] * o1[2] + o1[3] * o1[3]);
;                         u32x4 w; w.x = pkh(o0[0], o0[1]); w.y = pkh(o0[2], o0[3]); w.z = pkh(o1[0], o1[1]); w.w = pkh(o1[2], o1[3]);
;                         *(u32x4*)(h16 + off + bj * HALF) = w;
;                         if (h8) { u32x2 q; q.x = pk8(o0[0] * F8_SA, o0[1] * F8_SA, o0[2] * F8_SA, o0[3] * F8_SA); q.y = pk8(o1[0] * F8_SA, o1[1] * F8_SA, o1[2] * F8_SA, o1[3] * F8_SA); *(u32x2*)(h8 + off + bj * HALF) = q; } }
;                 }
;                 if (!out32 && !dry) { sq += __shfl_xor(sq, 16); sq += __shfl_xor(sq, 32); if (fq == 0) atomicAdd(ss_out + row, sq); }
.LBB0_413:
	s_or_b64 exec, exec, s[2:3]
	v_add_u32_e32 v50, 0x90, v148
	s_waitcnt lgkmcnt(0)
	v_ashrrev_i32_e32 v51, 31, v50
	v_lshlrev_b64 v[52:53], 11, v[50:51]
	v_lshl_add_u64 v[52:53], s[90:91], 0, v[52:53]
	v_lshl_add_u64 v[60:61], v[146:147], 1, v[52:53]
	s_waitcnt vmcnt(15)
	v_cvt_f32_f16_e32 v62, v212
	v_cvt_f32_f16_sdwa v63, v212 dst_sel:DWORD dst_unused:UNUSED_PAD src0_sel:WORD_1
	v_cvt_f32_f16_e32 v52, v213
	v_cvt_f32_f16_sdwa v53, v213 dst_sel:DWORD dst_unused:UNUSED_PAD src0_sel:WORD_1
	s_waitcnt vmcnt(14)
	v_cvt_f32_f16_e32 v66, v216
	v_cvt_f32_f16_sdwa v67, v216 dst_sel:DWORD dst_unused:UNUSED_PAD src0_sel:WORD_1
	v_cvt_f32_f16_e32 v56, v217
	v_cvt_f32_f16_sdwa v57, v217 dst_sel:DWORD dst_unused:UNUSED_PAD src0_sel:WORD_1
	v_cvt_f32_f16_e32 v64, v214
	v_cvt_f32_f16_sdwa v65, v214 dst_sel:DWORD dst_unused:UNUSED_PAD src0_sel:WORD_1
	v_cvt_f32_f16_e32 v54, v215
	v_cvt_f32_f16_sdwa v55, v215 dst_sel:DWORD dst_unused:UNUSED_PAD src0_sel:WORD_1
	v_cvt_f32_f16_e32 v68, v218
	v_cvt_f32_f16_sdwa v69, v218 dst_sel:DWORD dst_unused:UNUSED_PAD src0_sel:WORD_1
	v_cvt_f32_f16_e32 v58, v219
	v_cvt_f32_f16_sdwa v59, v219 dst_sel:DWORD dst_unused:UNUSED_PAD src0_sel:WORD_1
	v_pk_add_f32 v[46:47], v[46:47], v[62:63]
	v_pk_add_f32 v[48:49], v[48:49], v[52:53]
	v_pk_add_f32 v[38:39], v[38:39], v[66:67]
	v_pk_add_f32 v[40:41], v[40:41], v[56:57]
	v_pk_add_f32 v[42:43], v[42:43], v[64:65]
	v_pk_add_f32 v[44:45], v[44:45], v[54:55]
	v_pk_add_f32 v[52:53], v[34:35], v[68:69]
	v_pk_add_f32 v[54:55], v[36:37], v[58:59]
	v_pk_mul_f32 v[36:37], v[46:47], v[46:47]
	v_pk_mul_f32 v[56:57], v[48:49], v[48:49]
	v_cvt_pk_f16_f32 v34, v46, v47
	v_cvt_pk_f16_f32 v35, v48, v49
	v_pk_mul_f32 v[46:47], v[38:39], v[38:39]
	v_pk_mul_f32 v[48:49], v[40:41], v[40:41]
	v_pk_mul_f32 v[58:59], v[42:43], v[42:43]
	v_pk_mul_f32 v[64:65], v[52:53], v[52:53]
	v_add_f32_e32 v48, v48, v49
	v_add_f32_e32 v46, v46, v47
	v_add_f32_e32 v56, v56, v57
	v_add_f32_e32 v36, v36, v37
	v_pk_mul_f32 v[62:63], v[44:45], v[44:45]
	v_pk_mul_f32 v[66:67], v[54:55], v[54:55]
	v_add_f32_e32 v47, v64, v65
	v_add_f32_e32 v37, v58, v59
	v_add_f32_e32 v46, v46, v48
	v_add_f32_e32 v36, v36, v56
	v_add_f32_e32 v49, v66, v67
	v_add_f32_e32 v57, v62, v63
	v_add_f32_e32 v46, v47, v46
	v_add_f32_e32 v36, v37, v36
	v_add_f32_e32 v37, v49, v46
	v_add_f32_e32 v36, v57, v36
	v_add_f32_e32 v46, v36, v37
	ds_bpermute_b32 v47, v156, v46
	v_cvt_pk_f16_f32 v36, v42, v43
	v_cvt_pk_f16_f32 v37, v44, v45
	global_store_dwordx4 v[60:61], v[34:37], off
	s_waitcnt lgkmcnt(0)
	s_nop 0
	v_add_f32_e32 v34, v46, v47
	ds_bpermute_b32 v35, v116, v34
	v_cvt_pk_f16_f32 v36, v38, v39
	v_cvt_pk_f16_f32 v37, v40, v41
	v_cvt_pk_f16_f32 v38, v52, v53
	v_cvt_pk_f16_f32 v39, v54, v55
	global_store_dwordx4 v[60:61], v[36:39], off offset:256
	s_and_saveexec_b64 s[2:3], vcc
	s_cbranch_execz .LBB0_415
	v_lshl_add_u64 v[36:37], v[50:51], 2, s[18:19]
	s_waitcnt lgkmcnt(0)
	v_add_f32_e32 v34, v34, v35
	global_atomic_add_f32 v[36:37], v34, off
; __device__ __forceinline__ unsigned pkh(float lo, float hi) { f32x2 v = {lo, hi}; h16x2 h = __builtin_convertvector(v, h16x2); return __builtin_bit_cast(unsigned, h); }
; __device__ __forceinline__ unsigned pk8(float a, float b, float c, float d) { int w = __builtin_amdgcn_cvt_pk_fp8_f32(a, b, 0, false); w = __builtin_amdgcn_cvt_pk_fp8_f32(c, d, w, true); return (unsigned)w; }
;     __device__ __forceinline__ void operator()(f32x4 (&acc)[2][2][4][2], const Unit& u, const Order& S, int wr, int wc, int fr_, int fq_, LAS unsigned char*, int) const {
;     ...
;                 const int row = row0 + ai * HALF + m * 16; const size_t off = (size_t)row * DM + col0;
;                 float sq = 0.f;
; #pragma unroll
;                 for (int bj = 0; bj < 2; ++bj) {
;                     const h16x8 bs = *(const h16x8*)(h16 + off + bj * HALF);
;                     f32x4 o0 = acc[ai][bj][m][0] * pre, o1 = acc[ai][bj][m][1] * pre;
; #pragma unroll
;                     for (int e = 0; e < 4; ++e) { o0[e] += (float)bs[e]; o1[e] += (float)bs[4 + e]; }
;                     if (out32) { if (!dry) { __builtin_nontemporal_store(o0, (f32x4*)(out32 + off + bj * HALF)); __builtin_nontemporal_store(o1, (f32x4*)(out32 + off + bj * HALF + 4)); } }
;                     else if (!dry) {
;                         sq += (o0[0] * o0[0] + o0[1] * o0[1]) + (o0[2] * o0[2] + o0[3] * o0[3]) + (o1[0] * o1[0] + o1[1] * o1[1]) + (o1[2] * o1[2] + o1[3] * o1[3]);
;                         u32x4 w; w.x = pkh(o0[0], o0[1]); w.y = pkh(o0[2], o0[3]); w.z = pkh(o1[0], o1[1]); w.w = pkh(o1[2], o1[3]);
;                         *(u32x4*)(h16 + off + bj * HALF) = w;
;                         if (h8) { u32x2 q; q.x = pk8(o0[0] * F8_SA, o0[1] * F8_SA, o0[2] * F8_SA, o0[3] * F8_SA); q.y = pk8(o1[0] * F8_SA, o1[1] * F8_SA, o1[2] * F8_SA, o1[3] * F8_SA); *(u32x2*)(h8 + off + bj * HALF) = q; } }
;                 }
;                 if (!out32 && !dry) { sq += __shfl_xor(sq, 16); sq += __shfl_xor(sq, 32); if (fq == 0) atomicAdd(ss_out + row, sq); }
.LBB0_415:
	s_or_b64 exec, exec, s[2:3]
	v_add_u32_e32 v34, 0xa0, v148
	s_waitcnt lgkmcnt(0)
	v_ashrrev_i32_e32 v35, 31, v34
	v_lshlrev_b64 v[36:37], 11, v[34:35]
	v_lshl_add_u64 v[36:37], s[90:91], 0, v[36:37]
	v_lshl_add_u64 v[44:45], v[146:147], 1, v[36:37]
	s_waitcnt vmcnt(15)
	v_cvt_f32_f16_e32 v46, v240
	v_cvt_f32_f16_sdwa v47, v240 dst_sel:DWORD dst_unused:UNUSED_PAD src0_sel:WORD_1
	v_cvt_f32_f16_e32 v36, v241
	v_cvt_f32_f16_sdwa v37, v241 dst_sel:DWORD dst_unused:UNUSED_PAD src0_sel:WORD_1
	s_waitcnt vmcnt(14)
	v_cvt_f32_f16_e32 v50, v244
	v_cvt_f32_f16_sdwa v51, v244 dst_sel:DWORD dst_unused:UNUSED_PAD src0_sel:WORD_1
	v_cvt_f32_f16_e32 v40, v245
	v_cvt_f32_f16_sdwa v41, v245 dst_sel:DWORD dst_unused:UNUSED_PAD src0_sel:WORD_1
	v_cvt_f32_f16_e32 v48, v242
	v_cvt_f32_f16_sdwa v49, v242 dst_sel:DWORD dst_unused:UNUSED_PAD src0_sel:WORD_1
	v_cvt_f32_f16_e32 v38, v243
	v_cvt_f32_f16_sdwa v39, v243 dst_sel:DWORD dst_unused:UNUSED_PAD src0_sel:WORD_1
	v_cvt_f32_f16_e32 v52, v246
	v_cvt_f32_f16_sdwa v53, v246 dst_sel:DWORD dst_unused:UNUSED_PAD src0_sel:WORD_1
	v_cvt_f32_f16_e32 v42, v247
	v_cvt_f32_f16_sdwa v43, v247 dst_sel:DWORD dst_unused:UNUSED_PAD src0_sel:WORD_1
	v_pk_add_f32 v[30:31], v[30:31], v[46:47]
	v_pk_add_f32 v[32:33], v[32:33], v[36:37]
	v_pk_add_f32 v[22:23], v[22:23], v[50:51]
	v_pk_add_f32 v[24:25], v[24:25], v[40:41]
	v_pk_add_f32 v[26:27], v[26:27], v[48:49]
	v_pk_add_f32 v[28:29], v[28:29], v[38:39]
	v_pk_add_f32 v[36:37], v[18:19], v[52:53]
	v_pk_add_f32 v[38:39], v[20:21], v[42:43]
	v_pk_mul_f32 v[20:21], v[30:31], v[30:31]
	v_pk_mul_f32 v[40:41], v[32:33], v[32:33]
	v_cvt_pk_f16_f32 v18, v30, v31
	v_cvt_pk_f16_f32 v19, v32, v33
	v_pk_mul_f32 v[30:31], v[22:23], v[22:23]
	v_pk_mul_f32 v[32:33], v[24:25], v[24:25]
	v_pk_mul_f32 v[42:43], v[26:27], v[26:27]
	v_pk_mul_f32 v[48:49], v[36:37], v[36:37]
	v_add_f32_e32 v32, v32, v33
	v_add_f32_e32 v30, v30, v31
	v_add_f32_e32 v40, v40, v41
	v_add_f32_e32 v20, v20, v21
	v_pk_mul_f32 v[46:47], v[28:29], v[28:29]
	v_pk_mul_f32 v[50:51], v[38:39], v[38:39]
	v_add_f32_e32 v31, v48, v49
	v_add_f32_e32 v21, v42, v43
	v_add_f32_e32 v30, v30, v32
	v_add_f32_e32 v20, v20, v40
	v_add_f32_e32 v33, v50, v51
	v_add_f32_e32 v41, v46, v47
	v_add_f32_e32 v30, v31, v30
	v_add_f32_e32 v20, v21, v20
	v_add_f32_e32 v21, v33, v30
	v_add_f32_e32 v20, v41, v20
	v_add_f32_e32 v30, v20, v21
	ds_bpermute_b32 v31, v156, v30
	v_cvt_pk_f16_f32 v20, v26, v27
	v_cvt_pk_f16_f32 v21, v28, v29
	global_store_dwordx4 v[44:45], v[18:21], off
	s_waitcnt lgkmcnt(0)
	s_nop 0
	v_add_f32_e32 v18, v30, v31
	ds_bpermute_b32 v19, v116, v18
	v_cvt_pk_f16_f32 v20, v22, v23
	v_cvt_pk_f16_f32 v21, v24, v25
	v_cvt_pk_f16_f32 v22, v36, v37
	v_cvt_pk_f16_f32 v23, v38, v39
	global_store_dwordx4 v[44:45], v[20:23], off offset:256
	s_and_saveexec_b64 s[2:3], vcc
	s_cbranch_execz .LBB0_417
	v_lshl_add_u64 v[20:21], v[34:35], 2, s[18:19]
	s_waitcnt lgkmcnt(0)
	v_add_f32_e32 v18, v18, v19
	global_atomic_add_f32 v[20:21], v18, off
.LBB0_417:
	s_or_b64 exec, exec, s[2:3]
	v_add_u32_e32 v18, 0xb0, v148
	s_waitcnt lgkmcnt(0)
	v_ashrrev_i32_e32 v19, 31, v18
	v_lshlrev_b64 v[20:21], 11, v[18:19]
	v_lshl_add_u64 v[20:21], s[90:91], 0, v[20:21]
	v_lshl_add_u64 v[28:29], v[146:147], 1, v[20:21]
	s_waitcnt vmcnt(15)
	v_cvt_f32_f16_e32 v30, v248
	v_cvt_f32_f16_sdwa v31, v248 dst_sel:DWORD dst_unused:UNUSED_PAD src0_sel:WORD_1
	v_cvt_f32_f16_e32 v20, v249
	v_cvt_f32_f16_sdwa v21, v249 dst_sel:DWORD dst_unused:UNUSED_PAD src0_sel:WORD_1
	s_waitcnt vmcnt(14)
	v_cvt_f32_f16_e32 v34, v252
	v_cvt_f32_f16_sdwa v35, v252 dst_sel:DWORD dst_unused:UNUSED_PAD src0_sel:WORD_1
	v_cvt_f32_f16_e32 v24, v253
	v_cvt_f32_f16_sdwa v25, v253 dst_sel:DWORD dst_unused:UNUSED_PAD src0_sel:WORD_1
	v_cvt_f32_f16_e32 v32, v250
	v_cvt_f32_f16_sdwa v33, v250 dst_sel:DWORD dst_unused:UNUSED_PAD src0_sel:WORD_1
	v_cvt_f32_f16_e32 v22, v251
	v_cvt_f32_f16_sdwa v23, v251 dst_sel:DWORD dst_unused:UNUSED_PAD src0_sel:WORD_1
	v_cvt_f32_f16_e32 v36, v254
	v_cvt_f32_f16_sdwa v37, v254 dst_sel:DWORD dst_unused:UNUSED_PAD src0_sel:WORD_1
	v_cvt_f32_f16_e32 v26, v255
	v_cvt_f32_f16_sdwa v27, v255 dst_sel:DWORD dst_unused:UNUSED_PAD src0_sel:WORD_1
	v_pk_add_f32 v[14:15], v[14:15], v[30:31]
	v_pk_add_f32 v[16:17], v[16:17], v[20:21]
	v_pk_add_f32 v[6:7], v[6:7], v[34:35]
	v_pk_add_f32 v[8:9], v[8:9], v[24:25]
	v_pk_add_f32 v[10:11], v[10:11], v[32:33]
	v_pk_add_f32 v[12:13], v[12:13], v[22:23]
	v_pk_add_f32 v[20:21], v[2:3], v[36:37]
	v_pk_add_f32 v[22:23], v[4:5], v[26:27]
	v_pk_mul_f32 v[4:5], v[14:15], v[14:15]
	v_pk_mul_f32 v[24:25], v[16:17], v[16:17]
	v_cvt_pk_f16_f32 v2, v14, v15
	v_cvt_pk_f16_f32 v3, v16, v17
	v_pk_mul_f32 v[14:15], v[6:7], v[6:7]
	v_pk_mul_f32 v[16:17], v[8:9], v[8:9]
	v_pk_mul_f32 v[26:27], v[10:11], v[10:11]
	v_pk_mul_f32 v[32:33], v[20:21], v[20:21]
	v_add_f32_e32 v16, v16, v17
	v_add_f32_e32 v14, v14, v15
	v_add_f32_e32 v24, v24, v25
	v_add_f32_e32 v4, v4, v5
	v_pk_mul_f32 v[30:31], v[12:13], v[12:13]
	v_pk_mul_f32 v[34:35], v[22:23], v[22:23]
	v_add_f32_e32 v15, v32, v33
	v_add_f32_e32 v5, v26, v27
	v_add_f32_e32 v14, v14, v16
	v_add_f32_e32 v4, v4, v24
	v_add_f32_e32 v17, v34, v35
	v_add_f32_e32 v25, v30, v31
	v_add_f32_e32 v14, v15, v14
	v_add_f32_e32 v4, v5, v4
	v_add_f32_e32 v5, v17, v14
	v_add_f32_e32 v4, v25, v4
	v_add_f32_e32 v14, v4, v5
	ds_bpermute_b32 v15, v156, v14
	v_cvt_pk_f16_f32 v4, v10, v11
	v_cvt_pk_f16_f32 v5, v12, v13
	global_store_dwordx4 v[28:29], v[2:5], off
	s_waitcnt lgkmcnt(0)
	s_nop 0
	v_add_f32_e32 v2, v14, v15
	ds_bpermute_b32 v3, v116, v2
	v_cvt_pk_f16_f32 v4, v6, v7
	v_cvt_pk_f16_f32 v5, v8, v9
	v_cvt_pk_f16_f32 v6, v20, v21
	v_cvt_pk_f16_f32 v7, v22, v23
	global_store_dwordx4 v[28:29], v[4:7], off offset:256
	s_and_saveexec_b64 s[2:3], vcc
	s_cbranch_execz .LBB0_419
	v_lshl_add_u64 v[4:5], v[18:19], 2, s[18:19]
	s_waitcnt lgkmcnt(0)
	v_add_f32_e32 v2, v2, v3
	global_atomic_add_f32 v[4:5], v2, off

; __global__ void __launch_bounds__(NWAVES * 64, 2) fwd_kernel(Args args) {
;     extern __shared__ __attribute__((aligned(16))) unsigned char lds_raw[];
	.amdhsa_kernel _Z10fwd_kernel4Args
		.amdhsa_group_segment_fixed_size 0
		.amdhsa_private_segment_fixed_size 0
		.amdhsa_kernarg_size 448
		.amdhsa_user_sgpr_count 2
		.amdhsa_user_sgpr_dispatch_ptr 0
		.amdhsa_user_sgpr_queue_ptr 0
		.amdhsa_user_sgpr_kernarg_segment_ptr 1
		.amdhsa_user_sgpr_dispatch_id 0
		.amdhsa_user_sgpr_kernarg_preload_length 0
		.amdhsa_user_sgpr_kernarg_preload_offset 0
		.amdhsa_user_sgpr_private_segment_size 0
		.amdhsa_uses_dynamic_stack 0
		.amdhsa_enable_private_segment 0
		.amdhsa_system_sgpr_workgroup_id_x 1
		.amdhsa_system_sgpr_workgroup_id_y 0
		.amdhsa_system_sgpr_workgroup_id_z 0
		.amdhsa_system_sgpr_workgroup_info 0
		.amdhsa_system_vgpr_workitem_id 0
		.amdhsa_next_free_vgpr 256
		.amdhsa_next_free_sgpr 100
		.amdhsa_accum_offset 256
		.amdhsa_reserve_vcc 1
		.amdhsa_float_round_mode_32 0
		.amdhsa_float_round_mode_16_64 0
		.amdhsa_float_denorm_mode_32 3
		.amdhsa_float_denorm_mode_16_64 3
		.amdhsa_dx10_clamp 1
		.amdhsa_ieee_mode 1
		.amdhsa_fp16_overflow 0
		.amdhsa_tg_split 0
		.amdhsa_exception_fp_ieee_invalid_op 0
		.amdhsa_exception_fp_denorm_src 0
		.amdhsa_exception_fp_ieee_div_zero 0
		.amdhsa_exception_fp_ieee_overflow 0
		.amdhsa_exception_fp_ieee_underflow 0
		.amdhsa_exception_fp_ieee_inexact 0
		.amdhsa_exception_int_div_zero 0
	.end_amdhsa_kernel

; __global__ void __launch_bounds__(NWAVES * 64, 2) fwd_kernel(Args args) {
;     extern __shared__ __attribute__((aligned(16))) unsigned char lds_raw[];
amdhsa.kernels:
  - .agpr_count:     0
    .args:
      - .offset:         0
        .size:           192
        .value_kind:     by_value
      - .offset:         192
        .size:           4
        .value_kind:     hidden_block_count_x
      - .offset:         196
        .size:           4
        .value_kind:     hidden_block_count_y
      - .offset:         200
        .size:           4
        .value_kind:     hidden_block_count_z
      - .offset:         204
        .size:           2
        .value_kind:     hidden_group_size_x
      - .offset:         206
        .size:           2
        .value_kind:     hidden_group_size_y
      - .offset:         208
        .size:           2
        .value_kind:     hidden_group_size_z
      - .offset:         210
        .size:           2
        .value_kind:     hidden_remainder_x
      - .offset:         212
        .size:           2
        .value_kind:     hidden_remainder_y
      - .offset:         214
        .size:           2
        .value_kind:     hidden_remainder_z
      - .offset:         232
        .size:           8
        .value_kind:     hidden_global_offset_x
      - .offset:         240
        .size:           8
        .value_kind:     hidden_global_offset_y
      - .offset:         248
        .size:           8
        .value_kind:     hidden_global_offset_z
      - .offset:         256
        .size:           2
        .value_kind:     hidden_grid_dims
      - .offset:         312
        .size:           4
        .value_kind:     hidden_dynamic_lds_size
    .group_segment_fixed_size: 0
    .kernarg_segment_align: 8
    .kernarg_segment_size: 448
    .language:       OpenCL C
    .language_version:
      - 2
      - 0
    .max_flat_workgroup_size: 512
    .name:           _Z10fwd_kernel4Args
    .private_segment_fixed_size: 0
    .sgpr_count:     106
    .sgpr_spill_count: 152
    .symbol:         _Z10fwd_kernel4Args.kd
    .uniform_work_group_size: 1
    .uses_dynamic_stack: false
    .vgpr_count:     256
    .vgpr_spill_count: 0
    .wavefront_size: 64
